# s5_prompt step 1: 8 Win fragments requested before the Xc barrier (was 6), rest as the previous best
# speedup vs baseline: 1.0019x; 1.0016x over previous
; #define LAS __attribute__((address_space(3)))
; __device__ __forceinline__ void s5_prompt(const Args& a, LAS unsigned char* lds, int b, int g, int tid, int lane, int wave) {
;     ...
;     {
;         const int mt = wave & 3, nt0 = (wave >> 2) * 2;
;         const bf16_t* w0 = Win + (size_t)(32 * nt0 + r32) * 256 + 8 * hh;
;         bf16x8 bw[2][16];
;         {
;             u32x4 v[8];
; #pragma unroll
;             for (int i = 0; i < 8; ++i) { const int q = tid + 512 * i, t = q >> 1, half = q & 1; v[i] = *(const u32x4*)(U + (size_t)(b * SEQ + t) * DH + 16 * g + 8 * half); }
; #pragma unroll
;             for (int ks = 0; ks < 16; ++ks) { bw[0][ks] = *(const bf16x8*)(w0 + 16 * ks); bw[1][ks] = *(const bf16x8*)(w0 + 32 * 256 + 16 * ks); }
;             asm volatile("" ::: "memory");
; #pragma unroll
;             for (int i = 0; i < 8; ++i) { const int q = tid + 512 * i, t = q >> 1, half = q & 1; *(LAS u32x4*)(XCs + (t >> 4) * S5_PITCH + (t & 15) * 32 + 16 * half) = v[i]; }
;         }
;         __syncthreads();
.LBB0_559:
	s_lshl_b32 s0, s35, 3
	s_and_b32 s0, s0, 56
	s_bfe_u32 s1, s35, 0x30003
	s_or_b32 s36, s0, s1
	s_lshl_b32 s0, s36, 18
	s_add_u32 s0, s13, s0
	s_addc_u32 s1, s28, 0
	s_add_u32 s6, s0, 0x10000
	s_addc_u32 s7, s1, 0
	s_lshl_b32 s37, s35, 5
	s_and_b32 s37, s37, 0xfffff800
	v_readlane_b32 s48, v254, 40
	v_readlane_b32 s49, v254, 41
	v_lshlrev_b32_e32 v34, 4, v0
	s_nop 3
	s_lshl_b32 s50, s37, 11
	s_lshl_b32 s51, s36, 16
	s_add_u32 s48, s48, s50
	s_addc_u32 s49, s49, 0
	s_add_u32 s48, s48, s51
	s_addc_u32 s49, s49, 0
	s_mul_i32 s44, s36, 0x2400
	v_or_b32_e32 v2, s37, v162
	v_or_b32_e32 v6, s37, v185
	v_or_b32_e32 v8, s37, v186
	v_or_b32_e32 v14, s37, v187
	v_or_b32_e32 v16, s37, v188
	v_or_b32_e32 v22, s37, v189
	v_or_b32_e32 v24, s37, v190
	v_lshl_add_u64 v[36:37], v[168:169], 0, s[44:45]
	s_lshl_b32 s44, s36, 5
	v_ashrrev_i32_e32 v3, 31, v2
	v_ashrrev_i32_e32 v7, 31, v6
	v_ashrrev_i32_e32 v9, 31, v8
	v_ashrrev_i32_e32 v15, 31, v14
	v_ashrrev_i32_e32 v17, 31, v16
	v_ashrrev_i32_e32 v23, 31, v22
	v_ashrrev_i32_e32 v25, 31, v24
	v_lshl_add_u64 v[30:31], v[172:173], 0, s[44:45]
	v_lshlrev_b64 v[2:3], 11, v[2:3]
	v_lshlrev_b64 v[6:7], 11, v[6:7]
	v_lshlrev_b64 v[8:9], 11, v[8:9]
	v_lshlrev_b64 v[14:15], 11, v[14:15]
	v_lshlrev_b64 v[16:17], 11, v[16:17]
	v_lshlrev_b64 v[22:23], 11, v[22:23]
	v_lshlrev_b64 v[24:25], 11, v[24:25]
	v_lshl_add_u64 v[2:3], v[30:31], 0, v[2:3]
	v_lshl_add_u64 v[6:7], v[30:31], 0, v[6:7]
	v_lshl_add_u64 v[10:11], v[30:31], 0, v[8:9]
	v_lshl_add_u64 v[14:15], v[30:31], 0, v[14:15]
	v_lshl_add_u64 v[18:19], v[30:31], 0, v[16:17]
	v_lshl_add_u64 v[22:23], v[30:31], 0, v[22:23]
	v_lshl_add_u64 v[26:27], v[30:31], 0, v[24:25]
	global_load_dwordx4 v[2:5], v34, s[48:49]
	s_nop 0
	s_add_u32 s48, s48, 0x2000
	s_addc_u32 s49, s49, 0
	global_load_dwordx4 v[6:9], v34, s[48:49]
	s_nop 0
	s_add_u32 s48, s48, 0x2000
	s_addc_u32 s49, s49, 0
	global_load_dwordx4 v[10:13], v34, s[48:49]
	s_nop 0
	s_add_u32 s48, s48, 0x2000
	s_addc_u32 s49, s49, 0
	global_load_dwordx4 v[14:17], v34, s[48:49]
	s_nop 0
	s_add_u32 s48, s48, 0x2000
	s_addc_u32 s49, s49, 0
	global_load_dwordx4 v[18:21], v34, s[48:49]
	s_nop 0
	s_add_u32 s48, s48, 0x2000
	s_addc_u32 s49, s49, 0
	global_load_dwordx4 v[22:25], v34, s[48:49]
	s_nop 0
	s_add_u32 s48, s48, 0x2000
	s_addc_u32 s49, s49, 0
	global_load_dwordx4 v[26:29], v34, s[48:49]
	v_or_b32_e32 v32, s37, v191
	v_ashrrev_i32_e32 v33, 31, v32
	v_lshlrev_b64 v[32:33], 11, v[32:33]
	v_lshl_add_u64 v[30:31], v[30:31], 0, v[32:33]
	s_add_u32 s48, s48, 0x2000
	s_addc_u32 s49, s49, 0
	global_load_dwordx4 v[30:33], v34, s[48:49]
	v_readlane_b32 s38, v254, 12
	s_lshr_b32 s38, s38, 6
	s_lshr_b32 s39, s38, 2
	s_lshl_b32 s39, s39, 1
	s_and_b32 s38, s38, 3
	s_sub_i32 s39, s39, s38
	s_lshl_b32 s38, s38, 14
	v_lshl_add_u32 v35, v210, 4, s38
	global_load_dword v34, v[36:37], off offset:512
	global_load_dword v36, v[36:37], off offset:768
	s_add_u32 s48, s0, 0x0
	s_addc_u32 s49, s1, 0
	global_load_dwordx4 v[38:41], v35, s[48:49]
	s_add_u32 s50, s0, 0x400
	s_addc_u32 s51, s1, 0
	global_load_dwordx4 v[42:45], v35, s[50:51]
	s_add_u32 s48, s0, 0x800
	s_addc_u32 s49, s1, 0
	global_load_dwordx4 v[46:49], v35, s[48:49]
	s_add_u32 s50, s0, 0xc00
	s_addc_u32 s51, s1, 0
	global_load_dwordx4 v[50:53], v35, s[50:51]
	s_add_u32 s48, s0, 0x1000
	s_addc_u32 s49, s1, 0
	global_load_dwordx4 v[54:57], v35, s[48:49]
	s_add_u32 s50, s0, 0x1400
	s_addc_u32 s51, s1, 0
	global_load_dwordx4 v[58:61], v35, s[50:51]
	s_add_u32 s48, s0, 0x1800
	s_addc_u32 s49, s1, 0
	global_load_dwordx4 v[62:65], v35, s[48:49]
	s_add_u32 s50, s0, 0x1c00
	s_addc_u32 s51, s1, 0
	global_load_dwordx4 v[66:69], v35, s[50:51]
	s_mul_i32 s38, s39, 0x4200
	v_add_u32_e32 v118, s38, v207
	s_mul_i32 s38, s39, 0x4180
	v_add_u32_e32 v119, s38, v192
	s_andn2_b64 vcc, exec, s[68:69]
	s_waitcnt vmcnt(17)
	ds_write_b128 v199, v[2:5]
	s_waitcnt vmcnt(16)
	ds_write_b128 v200, v[6:9]
	s_waitcnt vmcnt(15)
	ds_write_b128 v201, v[10:13]
	s_waitcnt vmcnt(14)
	ds_write_b128 v202, v[14:17]
	s_waitcnt vmcnt(13)
	ds_write_b128 v203, v[18:21]
	s_waitcnt vmcnt(12)
	ds_write_b128 v204, v[22:25]
	s_waitcnt vmcnt(11)
	ds_write_b128 v205, v[26:29]
	s_waitcnt vmcnt(10)
	ds_write_b128 v206, v[30:33]
	s_waitcnt lgkmcnt(0)
	s_barrier
; #define LAS __attribute__((address_space(3)))
; #define MFMA32(a, b, c) __builtin_amdgcn_mfma_f32_32x32x16_bf16((a), (b), (c), 0, 0, 0)
; __device__ __forceinline__ void s5_prompt(const Args& a, LAS unsigned char* lds, int b, int g, int tid, int lane, int wave) {
;     ...
;         const LAS unsigned char* xa = XCs + (32 * mt + r32) * S5_PITCH + 16 * hh;
; #pragma unroll
;         for (int ks = 0; ks < 16; ++ks) { const bf16x8 af = *(const LAS bf16x8*)(xa + 32 * ks); acc0 = MFMA32(af, bw[0][ks], acc0); acc1 = MFMA32(af, bw[1][ks], acc1); }
;         LAS float* Z = (LAS float*)ZS;
; #pragma unroll
;         for (int i = 0; i < 16; ++i) { const int j = 32 * mt + (i & 3) + 8 * (i >> 2) + 4 * hh;
;             Z[j * (S5_PITCH / 4) + 32 * nt0 + r32] = acc0[i]; Z[j * (S5_PITCH / 4) + 32 * nt0 + 32 + r32] = acc1[i]; }
;     }
;     __syncthreads();
;     bf16x8 am[24];
;     { const int mt = wave; const bf16_t* mw = MW + (size_t)(32 * mt + r32) * 384 + 8 * hh;
; #pragma unroll
;       for (int ks = 0; ks < 16; ++ks) if (ks < 2 * mt + 2) am[ks] = *(const bf16x8*)(mw + 16 * ks);
	ds_read_b128 v[102:105], v118
	ds_read_b128 v[106:109], v118 offset:16896
	ds_read_b128 v[110:113], v118 offset:32
	ds_read_b128 v[114:117], v118 offset:16928
	s_waitcnt vmcnt(7) lgkmcnt(2)
	v_mfma_f32_32x32x16_bf16 v[2:17], v[102:105], v[38:41], 0
	v_mfma_f32_32x32x16_bf16 v[18:33], v[106:109], v[38:41], 0
	s_add_u32 s48, s0, 0x2000
	s_addc_u32 s49, s1, 0
	global_load_dwordx4 v[70:73], v35, s[48:49]
	ds_read_b128 v[102:105], v118 offset:64
	ds_read_b128 v[106:109], v118 offset:16960
	s_waitcnt vmcnt(7) lgkmcnt(2)
	v_mfma_f32_32x32x16_bf16 v[2:17], v[110:113], v[42:45], v[2:17]
	v_mfma_f32_32x32x16_bf16 v[18:33], v[114:117], v[42:45], v[18:33]
	s_add_u32 s50, s0, 0x2400
	s_addc_u32 s51, s1, 0
	global_load_dwordx4 v[74:77], v35, s[50:51]
	ds_read_b128 v[110:113], v118 offset:96
	ds_read_b128 v[114:117], v118 offset:16992
	s_waitcnt vmcnt(7) lgkmcnt(2)
	v_mfma_f32_32x32x16_bf16 v[2:17], v[102:105], v[46:49], v[2:17]
	v_mfma_f32_32x32x16_bf16 v[18:33], v[106:109], v[46:49], v[18:33]
	s_add_u32 s48, s0, 0x2800
	s_addc_u32 s49, s1, 0
	global_load_dwordx4 v[78:81], v35, s[48:49]
	ds_read_b128 v[102:105], v118 offset:128
	ds_read_b128 v[106:109], v118 offset:17024
	s_waitcnt vmcnt(7) lgkmcnt(2)
	v_mfma_f32_32x32x16_bf16 v[2:17], v[110:113], v[50:53], v[2:17]
	v_mfma_f32_32x32x16_bf16 v[18:33], v[114:117], v[50:53], v[18:33]
	s_add_u32 s50, s0, 0x2c00
	s_addc_u32 s51, s1, 0
	global_load_dwordx4 v[82:85], v35, s[50:51]
	ds_read_b128 v[110:113], v118 offset:160
	ds_read_b128 v[114:117], v118 offset:17056
	s_waitcnt vmcnt(7) lgkmcnt(2)
	v_mfma_f32_32x32x16_bf16 v[2:17], v[102:105], v[54:57], v[2:17]
	v_mfma_f32_32x32x16_bf16 v[18:33], v[106:109], v[54:57], v[18:33]
	s_add_u32 s48, s0, 0x3000
	s_addc_u32 s49, s1, 0
	global_load_dwordx4 v[86:89], v35, s[48:49]
	ds_read_b128 v[102:105], v118 offset:192
	ds_read_b128 v[106:109], v118 offset:17088
	s_waitcnt vmcnt(7) lgkmcnt(2)
	v_mfma_f32_32x32x16_bf16 v[2:17], v[110:113], v[58:61], v[2:17]
	v_mfma_f32_32x32x16_bf16 v[18:33], v[114:117], v[58:61], v[18:33]
	s_add_u32 s50, s0, 0x3400
	s_addc_u32 s51, s1, 0
	global_load_dwordx4 v[90:93], v35, s[50:51]
	ds_read_b128 v[110:113], v118 offset:224
	ds_read_b128 v[114:117], v118 offset:17120
	s_waitcnt vmcnt(7) lgkmcnt(2)
	v_mfma_f32_32x32x16_bf16 v[2:17], v[102:105], v[62:65], v[2:17]
	v_mfma_f32_32x32x16_bf16 v[18:33], v[106:109], v[62:65], v[18:33]
	s_add_u32 s48, s0, 0x3800
	s_addc_u32 s49, s1, 0
	global_load_dwordx4 v[94:97], v35, s[48:49]
	ds_read_b128 v[102:105], v118 offset:256
	ds_read_b128 v[106:109], v118 offset:17152
	s_waitcnt vmcnt(7) lgkmcnt(2)
	v_mfma_f32_32x32x16_bf16 v[2:17], v[110:113], v[66:69], v[2:17]
	v_mfma_f32_32x32x16_bf16 v[18:33], v[114:117], v[66:69], v[18:33]
	s_add_u32 s50, s0, 0x3c00
	s_addc_u32 s51, s1, 0
	global_load_dwordx4 v[98:101], v35, s[50:51]
	ds_read_b128 v[110:113], v118 offset:288
	ds_read_b128 v[114:117], v118 offset:17184
	s_waitcnt vmcnt(7) lgkmcnt(2)
	v_mfma_f32_32x32x16_bf16 v[2:17], v[102:105], v[70:73], v[2:17]
	v_mfma_f32_32x32x16_bf16 v[18:33], v[106:109], v[70:73], v[18:33]
	ds_read_b128 v[102:105], v118 offset:320
	ds_read_b128 v[106:109], v118 offset:17216
	s_waitcnt vmcnt(6) lgkmcnt(2)
	v_mfma_f32_32x32x16_bf16 v[2:17], v[110:113], v[74:77], v[2:17]
	v_mfma_f32_32x32x16_bf16 v[18:33], v[114:117], v[74:77], v[18:33]
	ds_read_b128 v[110:113], v118 offset:352
	ds_read_b128 v[114:117], v118 offset:17248
	s_waitcnt vmcnt(5) lgkmcnt(2)
	v_mfma_f32_32x32x16_bf16 v[2:17], v[102:105], v[78:81], v[2:17]
	v_mfma_f32_32x32x16_bf16 v[18:33], v[106:109], v[78:81], v[18:33]
	ds_read_b128 v[102:105], v118 offset:384
	ds_read_b128 v[106:109], v118 offset:17280
	s_waitcnt vmcnt(4) lgkmcnt(2)
	v_mfma_f32_32x32x16_bf16 v[2:17], v[110:113], v[82:85], v[2:17]
	v_mfma_f32_32x32x16_bf16 v[18:33], v[114:117], v[82:85], v[18:33]
	ds_read_b128 v[110:113], v118 offset:416
	ds_read_b128 v[114:117], v118 offset:17312
	s_waitcnt vmcnt(3) lgkmcnt(2)
	v_mfma_f32_32x32x16_bf16 v[2:17], v[102:105], v[86:89], v[2:17]
	v_mfma_f32_32x32x16_bf16 v[18:33], v[106:109], v[86:89], v[18:33]
	ds_read_b128 v[102:105], v118 offset:448
	ds_read_b128 v[106:109], v118 offset:17344
	s_waitcnt vmcnt(2) lgkmcnt(2)
	v_mfma_f32_32x32x16_bf16 v[2:17], v[110:113], v[90:93], v[2:17]
	v_mfma_f32_32x32x16_bf16 v[18:33], v[114:117], v[90:93], v[18:33]
	ds_read_b128 v[110:113], v118 offset:480
	ds_read_b128 v[114:117], v118 offset:17376
	s_waitcnt vmcnt(1) lgkmcnt(2)
	v_mfma_f32_32x32x16_bf16 v[2:17], v[102:105], v[94:97], v[2:17]
	v_mfma_f32_32x32x16_bf16 v[18:33], v[106:109], v[94:97], v[18:33]
	s_waitcnt vmcnt(0) lgkmcnt(0)
	v_mfma_f32_32x32x16_bf16 v[2:17], v[110:113], v[98:101], v[2:17]
	v_mfma_f32_32x32x16_bf16 v[18:33], v[114:117], v[98:101], v[18:33]
	s_nop 11
	ds_write_b32 v119, v2
	ds_write_b32 v119, v18 offset:16896
	ds_write_b32 v119, v3 offset:528
	ds_write_b32 v119, v19 offset:17424
	ds_write_b32 v119, v4 offset:1056
	ds_write_b32 v119, v20 offset:17952
	ds_write_b32 v119, v5 offset:1584
	ds_write_b32 v119, v21 offset:18480
	ds_write_b32 v119, v6 offset:4224
	ds_write_b32 v119, v22 offset:21120
	ds_write_b32 v119, v7 offset:4752
	ds_write_b32 v119, v23 offset:21648
	ds_write_b32 v119, v8 offset:5280
	ds_write_b32 v119, v24 offset:22176
	ds_write_b32 v119, v9 offset:5808
	ds_write_b32 v119, v25 offset:22704
	s_waitcnt lgkmcnt(6)
	ds_write_b32 v119, v10 offset:8448
	ds_write_b32 v119, v26 offset:25344
	ds_write_b32 v119, v11 offset:8976
	ds_write_b32 v119, v27 offset:25872
	ds_write_b32 v119, v12 offset:9504
	ds_write_b32 v119, v28 offset:26400
	ds_write_b32 v119, v13 offset:10032
	ds_write_b32 v119, v29 offset:26928
	ds_write_b32 v119, v14 offset:12672
	ds_write_b32 v119, v30 offset:29568
	ds_write_b32 v119, v15 offset:13200
	ds_write_b32 v119, v31 offset:30096
	ds_write_b32 v119, v16 offset:13728
	ds_write_b32 v119, v32 offset:30624
	ds_write_b32 v119, v17 offset:14256
	ds_write_b32 v119, v33 offset:31152
	v_lshl_add_u64 v[2:3], s[6:7], 0, v[174:175]
	v_lshl_add_u64 v[2:3], v[2:3], 0, v[166:167]
	s_waitcnt lgkmcnt(0)
	s_barrier
	s_mov_b64 s[50:51], s[6:7]
	s_mul_i32 s48, s3, 0x6000
	s_add_u32 s48, s50, s48
	s_addc_u32 s49, s51, 0
	v_lshlrev_b32_e32 v225, 4, v210
	v_add_u32_e32 v226, 0x1000, v225
	v_add_u32_e32 v227, 0x2000, v225
	v_add_u32_e32 v228, 0x3000, v225
	v_add_u32_e32 v229, 0x4000, v225
	v_add_u32_e32 v230, 0x5000, v225
	global_load_dwordx4 v[66:69], v225, s[48:49]
	global_load_dwordx4 v[70:73], v225, s[48:49] offset:1024
	v_cndmask_b32_e64 v4, 0, 1, s[68:69]
	v_cmp_ne_u32_e64 s[0:1], 1, v4
	s_cbranch_vccnz .LBB0_561
	global_load_dwordx4 v[74:77], v225, s[48:49] offset:2048
	s_and_b64 vcc, exec, s[0:1]
	s_cbranch_vccnz .LBB0_563
	s_branch .LBB0_562
